# in-proj rope epilogue: the second half's four cos/sin table loads of each 32-row block are issued with the first half's (separate registers) instead of after the first half's stores
# speedup vs baseline: 1.0019x; 1.0019x over previous
; template <int EPI>
; DI void phase_gemm(const Params& p, const GemmArgs& ga, char* lds) {
;     ...
; #pragma unroll
;         for (int mi = 0; mi < 4; ++mi) {
;           const int pos = pos0 + wm * 128 + mi * 32 + r;
;           float rs = 1.f;
;           if (nrm) {
;             float ss = 0.f;
; #pragma unroll
;             for (int i = 0; i < 16; ++i) ss += acc[mi][0][i] * acc[mi][0][i] + acc[mi][1][i] * acc[mi][1][i];
;             ss += __shfl_xor(ss, 32);
;             rs = rsqrtf(ss * (1.f / 64.f) + 1e-6f);
;           }
;           u16* q = QK + (size_t)(tokbase + pos) * QK0_LD + dcol + 8 * h;
;           const float* csr = cs + (size_t)pos * 64 + 8 * h;
; #pragma unroll
;           for (int jp = 0; jp < 2; ++jp) {
;             u32x2 v1[2], v2[2];
; #pragma unroll
;             for (int jj = 0; jj < 2; ++jj) {
;               const int j = 2 * jp + jj;
;               const float4 ca = *(const float4*)(csr + 16 * j);
;               const float4 cb = *(const float4*)(csr + 16 * j + 4);
.LBB0_338:
	s_or_b64 exec, exec, s[16:17]
	v_add_u32_e32 v152, s14, v189
	v_cndmask_b32_e32 v0, v223, v224, vcc
	v_mov_b32_e32 v161, v1
	v_ashrrev_i32_e32 v153, 31, v152
	v_lshl_add_u64 v[150:151], v[158:159], 0, v[0:1]
	v_lshl_add_u64 v[148:149], v[130:131], 0, v[160:161]
	v_lshlrev_b64 v[130:131], 8, v[152:153]
	v_lshl_add_u64 v[168:169], v[150:151], 0, v[130:131]
	global_load_dwordx4 v[130:133], v[168:169], off offset:16
	global_load_dwordx4 v[134:137], v[168:169], off
	global_load_dwordx4 v[226:229], v[168:169], off offset:144
	global_load_dwordx4 v[230:233], v[168:169], off offset:128
	global_load_dwordx4 v[234:237], v[168:169], off offset:208
	global_load_dwordx4 v[238:241], v[168:169], off offset:192
	global_load_dword v246, v[168:169], off offset:128
	s_movk_i32 s100, 0x2000
	v_add_co_u32_e64 v244, s[8:9], s100, v168
	v_addc_co_u32_e64 v245, s[8:9], 0, v169, s[8:9]
	global_load_dword v247, v[244:245], off
	global_load_dword v248, v[244:245], off offset:128
	v_mov_b32_e32 v176, v114
	s_and_saveexec_b64 s[8:9], vcc
	s_cbranch_execz .LBB0_340
	global_load_dwordx4 v[138:141], v[148:149], off
	s_waitcnt vmcnt(0)
	v_mov_b32_e32 v142, v139
	v_mov_b32_e32 v143, v140
	v_mul_f32_e32 v0, v166, v138
	v_pk_mul_f32 v[138:139], v[166:167], v[142:143] op_sel_hi:[0,1]
	v_mul_f32_e32 v176, v114, v0
	v_pk_mul_f32 v[172:173], v[172:173], v[138:139]
	v_mul_f32_e32 v0, v166, v141
	global_load_dwordx4 v[138:141], v[148:149], off offset:128
	v_mul_f32_e32 v147, v147, v0
	s_waitcnt vmcnt(0)
	v_pk_mul_f32 v[138:139], v[166:167], v[138:139] op_sel_hi:[0,1]
	v_pk_mul_f32 v[174:175], v[174:175], v[138:139]
	v_pk_mul_f32 v[138:139], v[166:167], v[140:141] op_sel_hi:[0,1]
	v_pk_mul_f32 v[170:171], v[170:171], v[138:139]

; template <int EPI>
; DI void phase_gemm(const Params& p, const GemmArgs& ga, char* lds) {
;     ...
;           for (int jp = 0; jp < 2; ++jp) {
;             u32x2 v1[2], v2[2];
; #pragma unroll
;             for (int jj = 0; jj < 2; ++jj) {
;               const int j = 2 * jp + jj;
;               const float4 ca = *(const float4*)(csr + 16 * j);
;               const float4 cb = *(const float4*)(csr + 16 * j + 4);
;               float x1[4], x2[4];
; #pragma unroll
;               for (int e = 0; e < 4; ++e) { x1[e] = acc[mi][0][4 * j + e]; x2[e] = acc[mi][1][4 * j + e]; }
;               if (nrm) {
;                 const float4 ga_ = *(const float4*)(gq + 8 * j + 4 * h);
;                 const float4 gb_ = *(const float4*)(gq + 32 + 8 * j + 4 * h);
;                 x1[0] *= rs * ga_.x; x1[1] *= rs * ga_.y; x1[2] *= rs * ga_.z; x1[3] *= rs * ga_.w;
;                 x2[0] *= rs * gb_.x; x2[1] *= rs * gb_.y; x2[2] *= rs * gb_.z; x2[3] *= rs * gb_.w;
;               }
;               const float cc[4] = {ca.x, ca.z, cb.x, cb.z};
;               const float sn[4] = {ca.y, ca.w, cb.y, cb.w};
;               float y1[4], y2[4];
; #pragma unroll
;               for (int e = 0; e < 4; ++e) {
;                 y1[e] = (x1[e] * cc[e] - x2[e] * sn[e]) * osc;
;                 y2[e] = (x2[e] * cc[e] + x1[e] * sn[e]) * osc;
;               }
;               v1[jj] = (u32x2){pk_bf16(y1[0], y1[1]), pk_bf16(y1[2], y1[3])};
;               v2[jj] = (u32x2){pk_bf16(y2[0], y2[1]), pk_bf16(y2[2], y2[3])};
;             }
;             half_swap(v1[0], v1[1]);
;             half_swap(v2[0], v2[1]);
;             u32x4 w1 = {v1[0].x, v1[0].y, v1[1].x, v1[1].y};
;             u32x4 w2 = {v2[0].x, v2[0].y, v2[1].x, v2[1].y};
;             *(u32x4*)(q + 16 * jp) = w1;
;             *(u32x4*)(q + 32 + 16 * jp) = w2;
.LBB0_342:
	s_or_b64 exec, exec, s[8:9]
	s_waitcnt vmcnt(2)
	v_mov_b32_e32 v195, v136
	v_mov_b32_e32 v197, v136
	v_mov_b32_e32 v136, v135
	v_mov_b32_e32 v194, v135
	v_pk_mov_b32 v[198:199], v[172:173], v[172:173] op_sel:[1,0]
	v_pk_mul_f32 v[200:201], v[136:137], v[174:175]
	v_mov_b32_e32 v135, v137
	v_mov_b32_e32 v137, v132
	v_mov_b32_e32 v132, v131
	v_mov_b32_e32 v196, v134
	v_mov_b32_e32 v177, v199
	v_mov_b32_e32 v136, v130
	v_mov_b32_e32 v199, v147
	v_pk_mul_f32 v[130:131], v[132:133], v[170:171]
	v_pk_fma_f32 v[196:197], v[196:197], v[176:177], v[200:201] neg_lo:[0,0,1] neg_hi:[0,0,1]
	v_mov_b32_e32 v177, v175
	v_pk_fma_f32 v[130:131], v[136:137], v[198:199], v[130:131] neg_lo:[0,0,1] neg_hi:[0,0,1]
	v_pk_mul_f32 v[176:177], v[194:195], v[176:177]
	v_mov_b32_e32 v175, v172
	v_pk_mul_f32 v[172:173], v[146:147], v[130:131] op_sel_hi:[0,1]
	v_pk_mul_f32 v[130:131], v[136:137], v[170:171]
	v_pk_fma_f32 v[134:135], v[134:135], v[174:175], v[176:177]
	v_pk_fma_f32 v[130:131], v[132:133], v[198:199], v[130:131]
	v_pk_mul_f32 v[134:135], v[146:147], v[134:135] op_sel_hi:[0,1]
	v_pk_mul_f32 v[132:133], v[146:147], v[130:131] op_sel_hi:[0,1]
	v_cvt_pk_bf16_f32 v134, v134, v135
	v_cvt_pk_bf16_f32 v135, v132, v133
	s_waitcnt vmcnt(0)
	v_mov_b32_e32 v133, v144
	v_mov_b32_e32 v144, v143
	v_mov_b32_e32 v132, v142
	v_pk_mul_f32 v[136:137], v[144:145], v[182:183]
	v_pk_mul_f32 v[196:197], v[146:147], v[196:197] op_sel_hi:[0,1]
	v_pk_fma_f32 v[136:137], v[132:133], v[186:187], v[136:137] neg_lo:[0,0,1] neg_hi:[0,0,1]
	v_pk_mul_f32 v[132:133], v[132:133], v[182:183]
	v_ashrrev_i32_e32 v165, 31, v164
	v_pk_fma_f32 v[132:133], v[144:145], v[186:187], v[132:133]
	v_pk_mul_f32 v[136:137], v[146:147], v[136:137] op_sel_hi:[0,1]
	v_pk_mul_f32 v[142:143], v[146:147], v[132:133] op_sel_hi:[0,1]
	v_mov_b32_e32 v133, v140
	v_mov_b32_e32 v140, v139
	v_mov_b32_e32 v132, v138
	v_pk_mul_f32 v[138:139], v[140:141], v[178:179]
	v_cvt_pk_bf16_f32 v130, v196, v197
	v_pk_fma_f32 v[138:139], v[132:133], v[180:181], v[138:139] neg_lo:[0,0,1] neg_hi:[0,0,1]
	v_pk_mul_f32 v[132:133], v[132:133], v[178:179]
	v_pk_mul_f32 v[138:139], v[146:147], v[138:139] op_sel_hi:[0,1]
	v_pk_fma_f32 v[132:133], v[140:141], v[180:181], v[132:133]
	v_cvt_pk_bf16_f32 v131, v172, v173
	v_lshl_add_u64 v[164:165], v[164:165], 1, v[156:157]
	v_add_u32_e32 v0, s12, v189
	v_pk_mul_f32 v[140:141], v[146:147], v[132:133] op_sel_hi:[0,1]
	v_cvt_pk_bf16_f32 v132, v136, v137
	v_cvt_pk_bf16_f32 v133, v138, v139
	v_mad_i64_i32 v[170:171], s[8:9], v0, s96, v[164:165]
	v_cvt_pk_bf16_f32 v136, v142, v143
	v_cvt_pk_bf16_f32 v137, v140, v141
	v_permlane32_swap_b32_e32 v130, v132
	v_permlane32_swap_b32_e32 v131, v133
	v_permlane32_swap_b32_e32 v134, v136
	v_permlane32_swap_b32_e32 v135, v137
	global_store_dwordx4 v[170:171], v[130:133], off
	global_store_dwordx4 v[170:171], v[134:137], off offset:64
	v_mov_b32_e32 v176, v90
	v_mov_b32_e32 v177, v91
	v_mov_b32_e32 v172, v92
	v_mov_b32_e32 v173, v93
	v_mov_b32_e32 v178, v122
	v_mov_b32_e32 v179, v123
	v_mov_b32_e32 v174, v124
	v_mov_b32_e32 v175, v125
	s_and_saveexec_b64 s[8:9], vcc
	s_cbranch_execz .LBB0_344
	global_load_dwordx4 v[138:141], v[148:149], off offset:64
	global_load_dwordx4 v[142:145], v[148:149], off offset:192
	s_waitcnt vmcnt(1)
	v_pk_mul_f32 v[138:139], v[166:167], v[138:139] op_sel_hi:[0,1]
	v_pk_mul_f32 v[140:141], v[166:167], v[140:141] op_sel_hi:[0,1]
	s_waitcnt vmcnt(0)
	v_pk_mul_f32 v[142:143], v[166:167], v[142:143] op_sel_hi:[0,1]
	v_pk_mul_f32 v[144:145], v[166:167], v[144:145] op_sel_hi:[0,1]
	v_pk_mul_f32 v[178:179], v[122:123], v[138:139]
	v_pk_mul_f32 v[174:175], v[124:125], v[140:141]
	v_pk_mul_f32 v[176:177], v[90:91], v[142:143]
	v_pk_mul_f32 v[172:173], v[92:93], v[144:145]
.LBB0_344:
	s_or_b64 exec, exec, s[8:9]
	v_mov_b32_e32 v182, v94
	v_mov_b32_e32 v183, v95
	v_mov_b32_e32 v168, v96
	v_mov_b32_e32 v169, v97
	v_mov_b32_e32 v186, v126
	v_mov_b32_e32 v187, v127
	v_mov_b32_e32 v180, v128
	v_mov_b32_e32 v181, v129
	s_and_saveexec_b64 s[8:9], vcc
	s_cbranch_execz .LBB0_346
	global_load_dwordx4 v[180:183], v[148:149], off offset:96
	global_load_dwordx4 v[194:197], v[148:149], off offset:224
	s_waitcnt vmcnt(1)
	v_pk_mul_f32 v[168:169], v[166:167], v[180:181] op_sel_hi:[0,1]
	v_pk_mul_f32 v[180:181], v[166:167], v[182:183] op_sel_hi:[0,1]
	s_waitcnt vmcnt(0)
	v_pk_mul_f32 v[182:183], v[166:167], v[194:195] op_sel_hi:[0,1]
	v_pk_mul_f32 v[166:167], v[166:167], v[196:197] op_sel_hi:[0,1]
	v_pk_mul_f32 v[186:187], v[126:127], v[168:169]
	v_pk_mul_f32 v[180:181], v[128:129], v[180:181]
	v_pk_mul_f32 v[182:183], v[94:95], v[182:183]
	v_pk_mul_f32 v[168:169], v[96:97], v[166:167]
; template <int EPI>
; DI void phase_gemm(const Params& p, const GemmArgs& ga, char* lds) {
;     ...
;         for (int mi = 0; mi < 4; ++mi) {
;           const int pos = pos0 + wm * 128 + mi * 32 + r;
;           float rs = 1.f;
;           if (nrm) {
;             float ss = 0.f;
; #pragma unroll
;             for (int i = 0; i < 16; ++i) ss += acc[mi][0][i] * acc[mi][0][i] + acc[mi][1][i] * acc[mi][1][i];
;             ss += __shfl_xor(ss, 32);
;             rs = rsqrtf(ss * (1.f / 64.f) + 1e-6f);
;           }
;           u16* q = QK + (size_t)(tokbase + pos) * QK0_LD + dcol + 8 * h;
;           const float* csr = cs + (size_t)pos * 64 + 8 * h;
; #pragma unroll
;           for (int jp = 0; jp < 2; ++jp) {
;             u32x2 v1[2], v2[2];
; #pragma unroll
;             for (int jj = 0; jj < 2; ++jj) {
;               const int j = 2 * jp + jj;
;               const float4 ca = *(const float4*)(csr + 16 * j);
;               const float4 cb = *(const float4*)(csr + 16 * j + 4);
;               float x1[4], x2[4];
; #pragma unroll
;               for (int e = 0; e < 4; ++e) { x1[e] = acc[mi][0][4 * j + e]; x2[e] = acc[mi][1][4 * j + e]; }
;               if (nrm) {
;                 const float4 ga_ = *(const float4*)(gq + 8 * j + 4 * h);
;                 const float4 gb_ = *(const float4*)(gq + 32 + 8 * j + 4 * h);
;                 x1[0] *= rs * ga_.x; x1[1] *= rs * ga_.y; x1[2] *= rs * ga_.z; x1[3] *= rs * ga_.w;
;                 x2[0] *= rs * gb_.x; x2[1] *= rs * gb_.y; x2[2] *= rs * gb_.z; x2[3] *= rs * gb_.w;
;               }
;               const float cc[4] = {ca.x, ca.z, cb.x, cb.z};
;               const float sn[4] = {ca.y, ca.w, cb.y, cb.w};
;               float y1[4], y2[4];
; #pragma unroll
;               for (int e = 0; e < 4; ++e) {
;                 y1[e] = (x1[e] * cc[e] - x2[e] * sn[e]) * osc;
;                 y2[e] = (x2[e] * cc[e] + x1[e] * sn[e]) * osc;
;               }
;               v1[jj] = (u32x2){pk_bf16(y1[0], y1[1]), pk_bf16(y1[2], y1[3])};
;               v2[jj] = (u32x2){pk_bf16(y2[0], y2[1]), pk_bf16(y2[2], y2[3])};
;             }
;             half_swap(v1[0], v1[1]);
;             half_swap(v2[0], v2[1]);
;             u32x4 w1 = {v1[0].x, v1[0].y, v1[1].x, v1[1].y};
;             u32x4 w2 = {v2[0].x, v2[0].y, v2[1].x, v2[1].y};
;             *(u32x4*)(q + 16 * jp) = w1;
;             *(u32x4*)(q + 32 + 16 * jp) = w2;
.LBB0_346:
	s_or_b64 exec, exec, s[8:9]
	s_waitcnt vmcnt(2)
	v_mov_b32_e32 v167, v232
	v_mov_b32_e32 v232, v231
	v_mov_b32_e32 v166, v230
	v_pk_mul_f32 v[230:231], v[232:233], v[176:177]
	v_mov_b32_e32 v147, v146
	v_pk_fma_f32 v[230:231], v[166:167], v[178:179], v[230:231] neg_lo:[0,0,1] neg_hi:[0,0,1]
	v_pk_mul_f32 v[166:167], v[166:167], v[176:177]
	v_pk_mul_f32 v[230:231], v[146:147], v[230:231]
	v_pk_fma_f32 v[232:233], v[232:233], v[178:179], v[166:167]
	v_mov_b32_e32 v167, v228
	v_mov_b32_e32 v228, v227
	v_mov_b32_e32 v166, v226
	v_pk_mul_f32 v[226:227], v[228:229], v[172:173]
	v_pk_mul_f32 v[232:233], v[146:147], v[232:233]
	v_pk_fma_f32 v[226:227], v[166:167], v[174:175], v[226:227] neg_lo:[0,0,1] neg_hi:[0,0,1]
	v_mov_b32_e32 v153, v101
	v_pk_mul_f32 v[176:177], v[146:147], v[226:227]
	v_pk_mul_f32 v[226:227], v[166:167], v[172:173]
	v_mov_b64_e32 v[172:173], v[50:51]
	v_pk_fma_f32 v[226:227], v[228:229], v[174:175], v[226:227]
	s_nop 0
	v_pk_mul_f32 v[228:229], v[146:147], v[226:227]
	v_cvt_pk_bf16_f32 v226, v230, v231
	v_cvt_pk_bf16_f32 v231, v228, v229
	s_waitcnt vmcnt(0)
	v_mov_b32_e32 v229, v240
	v_mov_b32_e32 v240, v239
	v_cvt_pk_bf16_f32 v230, v232, v233
	v_mov_b32_e32 v228, v238
	v_pk_mul_f32 v[232:233], v[240:241], v[182:183]
	v_cvt_pk_bf16_f32 v227, v176, v177
	v_pk_fma_f32 v[232:233], v[228:229], v[186:187], v[232:233] neg_lo:[0,0,1] neg_hi:[0,0,1]
	v_pk_mul_f32 v[228:229], v[228:229], v[182:183]
	v_pk_mul_f32 v[232:233], v[146:147], v[232:233]
	v_pk_fma_f32 v[228:229], v[240:241], v[186:187], v[228:229]
	s_nop 0
	v_pk_mul_f32 v[238:239], v[146:147], v[228:229]
	v_mov_b32_e32 v229, v236
	v_mov_b32_e32 v236, v235
	v_mov_b32_e32 v228, v234
	v_pk_mul_f32 v[234:235], v[236:237], v[168:169]
	s_nop 0
	v_pk_fma_f32 v[234:235], v[228:229], v[180:181], v[234:235] neg_lo:[0,0,1] neg_hi:[0,0,1]
	v_pk_mul_f32 v[228:229], v[228:229], v[168:169]
	v_pk_mul_f32 v[234:235], v[146:147], v[234:235]
	v_pk_fma_f32 v[228:229], v[236:237], v[180:181], v[228:229]
	v_mov_b64_e32 v[168:169], v[52:53]
	v_pk_mul_f32 v[236:237], v[146:147], v[228:229]
	v_cvt_pk_bf16_f32 v228, v232, v233
	v_cvt_pk_bf16_f32 v229, v234, v235
	v_cvt_pk_bf16_f32 v232, v238, v239
	v_cvt_pk_bf16_f32 v233, v236, v237
	v_permlane32_swap_b32_e32 v226, v228
	v_permlane32_swap_b32_e32 v227, v229
	v_permlane32_swap_b32_e32 v230, v232
	v_permlane32_swap_b32_e32 v231, v233
	global_store_dwordx4 v[170:171], v[226:229], off offset:32
	global_store_dwordx4 v[170:171], v[230:233], off offset:96
	v_mov_b32_e32 v170, v99
	v_mov_b32_e32 v171, v100
	s_and_saveexec_b64 s[8:9], s[6:7]
	s_xor_b64 s[8:9], exec, s[8:9]
	v_mov_b32_e32 v170, v99
	v_mov_b32_e32 v171, v100
	v_mov_b64_e32 v[168:169], v[52:53]
	v_mov_b64_e32 v[172:173], v[50:51]
	v_mov_b32_e32 v153, v101
	s_or_saveexec_b64 s[12:13], s[8:9]
	v_mov_b32_e32 v0, 1.0
	s_xor_b64 exec, exec, s[12:13]
	s_cbranch_execz .LBB0_350
	v_mul_f32_e32 v0, v98, v98
	v_mul_f32_e32 v130, v99, v99
	v_fmac_f32_e32 v0, v50, v50
	v_fmac_f32_e32 v130, v51, v51
	v_add_f32_e32 v0, v0, v130
	v_mul_f32_e32 v130, v100, v100
	v_fmac_f32_e32 v130, v52, v52
	v_add_f32_e32 v0, v130, v0
	v_mul_f32_e32 v130, v101, v101
	v_fmac_f32_e32 v130, v53, v53
	v_add_f32_e32 v0, v130, v0
	v_mul_f32_e32 v130, v102, v102
	v_fmac_f32_e32 v130, v54, v54
	v_add_f32_e32 v0, v130, v0
	v_mul_f32_e32 v130, v103, v103
	v_fmac_f32_e32 v130, v55, v55
	v_add_f32_e32 v0, v130, v0
	v_pk_mul_f32 v[130:131], v[104:105], v[104:105]
	v_pk_mul_f32 v[132:133], v[106:107], v[106:107]
	v_pk_fma_f32 v[130:131], v[56:57], v[56:57], v[130:131]
	v_pk_fma_f32 v[132:133], v[58:59], v[58:59], v[132:133]
	v_add_f32_e32 v0, v130, v0
	v_add_f32_e32 v0, v131, v0
	v_pk_mul_f32 v[134:135], v[108:109], v[108:109]
	v_add_f32_e32 v0, v132, v0
	v_pk_fma_f32 v[134:135], v[60:61], v[60:61], v[134:135]
	v_add_f32_e32 v0, v133, v0
	v_pk_mul_f32 v[136:137], v[110:111], v[110:111]
	v_add_f32_e32 v0, v134, v0
	v_pk_fma_f32 v[136:137], v[62:63], v[62:63], v[136:137]
	v_add_f32_e32 v0, v135, v0
	v_pk_mul_f32 v[138:139], v[112:113], v[112:113]
	v_add_f32_e32 v0, v136, v0
	v_pk_fma_f32 v[138:139], v[64:65], v[64:65], v[138:139]
	v_add_f32_e32 v0, v137, v0
	v_cmp_lt_i32_e64 s[8:9], v214, v208
	v_add_f32_e32 v0, v138, v0
	v_add_f32_e32 v0, v139, v0
	v_cndmask_b32_e64 v130, v207, v214, s[8:9]
	v_lshlrev_b32_e32 v130, 2, v130
	ds_bpermute_b32 v130, v130, v0
	s_waitcnt lgkmcnt(0)
	v_add_f32_e32 v0, v0, v130
	v_fmamk_f32 v0, v0, 0x3c800000, v205
	v_mul_f32_e32 v130, 0x4b800000, v0
	v_cmp_gt_f32_e64 s[8:9], s49, v0
	s_nop 1
	v_cndmask_b32_e64 v0, v0, v130, s[8:9]
	v_rsq_f32_e32 v0, v0
	s_nop 0
	v_mul_f32_e32 v130, 0x45800000, v0
	v_cndmask_b32_e64 v0, v0, v130, s[8:9]
.LBB0_350:
	s_or_b64 exec, exec, s[12:13]
	v_or_b32_e32 v174, 32, v152
	v_ashrrev_i32_e32 v175, 31, v174
	v_lshlrev_b64 v[130:131], 8, v[174:175]
	v_lshl_add_u64 v[166:167], v[150:151], 0, v[130:131]
	global_load_dwordx4 v[130:133], v[166:167], off offset:16
	global_load_dwordx4 v[134:137], v[166:167], off
	global_load_dwordx4 v[226:229], v[166:167], off offset:144
	global_load_dwordx4 v[230:233], v[166:167], off offset:128
	global_load_dwordx4 v[234:237], v[166:167], off offset:208
	global_load_dwordx4 v[238:241], v[166:167], off offset:192
	global_load_dword v246, v[166:167], off offset:128
	s_movk_i32 s100, 0x2000
	v_add_co_u32_e64 v244, s[8:9], s100, v166
	v_addc_co_u32_e64 v245, s[8:9], 0, v167, s[8:9]
	global_load_dword v247, v[244:245], off
	global_load_dword v248, v[244:245], off offset:128
	v_mov_b32_e32 v176, v98
	s_and_saveexec_b64 s[8:9], vcc
	s_cbranch_execz .LBB0_352
	global_load_dwordx4 v[138:141], v[148:149], off
	s_waitcnt vmcnt(0)
	v_mov_b32_e32 v142, v139
	v_mov_b32_e32 v143, v140
	v_mul_f32_e32 v138, v0, v138
	v_mul_f32_e32 v176, v98, v138
	v_pk_mul_f32 v[138:139], v[0:1], v[142:143] op_sel_hi:[0,1]
	v_pk_mul_f32 v[170:171], v[170:171], v[138:139]
	v_mul_f32_e32 v138, v0, v141
	v_mul_f32_e32 v153, v153, v138
	global_load_dwordx4 v[138:141], v[148:149], off offset:128
	s_waitcnt vmcnt(0)
	v_pk_mul_f32 v[138:139], v[0:1], v[138:139] op_sel_hi:[0,1]
	v_pk_mul_f32 v[172:173], v[172:173], v[138:139]
	v_pk_mul_f32 v[138:139], v[0:1], v[140:141] op_sel_hi:[0,1]
	v_pk_mul_f32 v[168:169], v[168:169], v[138:139]

; template <int EPI>
; DI void phase_gemm(const Params& p, const GemmArgs& ga, char* lds) {
;     ...
;           for (int jp = 0; jp < 2; ++jp) {
;             u32x2 v1[2], v2[2];
; #pragma unroll
;             for (int jj = 0; jj < 2; ++jj) {
;               const int j = 2 * jp + jj;
;               const float4 ca = *(const float4*)(csr + 16 * j);
;               const float4 cb = *(const float4*)(csr + 16 * j + 4);
;               float x1[4], x2[4];
; #pragma unroll
;               for (int e = 0; e < 4; ++e) { x1[e] = acc[mi][0][4 * j + e]; x2[e] = acc[mi][1][4 * j + e]; }
;               if (nrm) {
;                 const float4 ga_ = *(const float4*)(gq + 8 * j + 4 * h);
;                 const float4 gb_ = *(const float4*)(gq + 32 + 8 * j + 4 * h);
;                 x1[0] *= rs * ga_.x; x1[1] *= rs * ga_.y; x1[2] *= rs * ga_.z; x1[3] *= rs * ga_.w;
;                 x2[0] *= rs * gb_.x; x2[1] *= rs * gb_.y; x2[2] *= rs * gb_.z; x2[3] *= rs * gb_.w;
;               }
;               const float cc[4] = {ca.x, ca.z, cb.x, cb.z};
;               const float sn[4] = {ca.y, ca.w, cb.y, cb.w};
;               float y1[4], y2[4];
; #pragma unroll
;               for (int e = 0; e < 4; ++e) {
;                 y1[e] = (x1[e] * cc[e] - x2[e] * sn[e]) * osc;
;                 y2[e] = (x2[e] * cc[e] + x1[e] * sn[e]) * osc;
;               }
;               v1[jj] = (u32x2){pk_bf16(y1[0], y1[1]), pk_bf16(y1[2], y1[3])};
;               v2[jj] = (u32x2){pk_bf16(y2[0], y2[1]), pk_bf16(y2[2], y2[3])};
;             }
;             half_swap(v1[0], v1[1]);
;             half_swap(v2[0], v2[1]);
;             u32x4 w1 = {v1[0].x, v1[0].y, v1[1].x, v1[1].y};
;             u32x4 w2 = {v2[0].x, v2[0].y, v2[1].x, v2[1].y};
;             *(u32x4*)(q + 16 * jp) = w1;
;             *(u32x4*)(q + 32 + 16 * jp) = w2;
.LBB0_354:
	s_or_b64 exec, exec, s[8:9]
	s_waitcnt vmcnt(2)
	v_mov_b32_e32 v195, v136
	v_mov_b32_e32 v197, v136
	v_mov_b32_e32 v136, v135
	v_mov_b32_e32 v194, v135
	v_pk_mov_b32 v[198:199], v[170:171], v[170:171] op_sel:[1,0]
	v_pk_mul_f32 v[200:201], v[136:137], v[172:173]
	v_mov_b32_e32 v135, v137
	v_mov_b32_e32 v137, v132
	v_mov_b32_e32 v132, v131
	v_mov_b32_e32 v196, v134
	v_mov_b32_e32 v177, v199
	v_mov_b32_e32 v136, v130
	v_mov_b32_e32 v199, v153
	v_pk_mul_f32 v[130:131], v[132:133], v[168:169]
	v_pk_fma_f32 v[196:197], v[196:197], v[176:177], v[200:201] neg_lo:[0,0,1] neg_hi:[0,0,1]
	v_mov_b32_e32 v177, v173
	v_pk_fma_f32 v[130:131], v[136:137], v[198:199], v[130:131] neg_lo:[0,0,1] neg_hi:[0,0,1]
	v_pk_mul_f32 v[176:177], v[194:195], v[176:177]
	v_mov_b32_e32 v173, v170
	v_pk_mul_f32 v[170:171], v[146:147], v[130:131]
	v_pk_mul_f32 v[130:131], v[136:137], v[168:169]
	v_pk_fma_f32 v[134:135], v[134:135], v[172:173], v[176:177]
	v_pk_fma_f32 v[130:131], v[132:133], v[198:199], v[130:131]
	v_pk_mul_f32 v[134:135], v[146:147], v[134:135]
	v_pk_mul_f32 v[132:133], v[146:147], v[130:131]
	v_cvt_pk_bf16_f32 v134, v134, v135
	v_cvt_pk_bf16_f32 v135, v132, v133
	v_add_u32_e32 v132, s20, v174
	s_waitcnt vmcnt(0)
	v_mov_b32_e32 v133, v144
	v_mov_b32_e32 v144, v143
	v_mad_i64_i32 v[168:169], s[8:9], v132, s96, v[164:165]
	v_mov_b32_e32 v132, v142
	v_pk_mul_f32 v[136:137], v[144:145], v[182:183]
	v_pk_mul_f32 v[196:197], v[146:147], v[196:197]
	v_pk_fma_f32 v[136:137], v[132:133], v[186:187], v[136:137] neg_lo:[0,0,1] neg_hi:[0,0,1]
	v_pk_mul_f32 v[132:133], v[132:133], v[182:183]
	v_pk_mul_f32 v[136:137], v[146:147], v[136:137]
	v_pk_fma_f32 v[132:133], v[144:145], v[186:187], v[132:133]
	v_cvt_pk_bf16_f32 v130, v196, v197
	v_pk_mul_f32 v[142:143], v[146:147], v[132:133]
	v_mov_b32_e32 v133, v140
	v_mov_b32_e32 v140, v139
	v_mov_b32_e32 v132, v138
	v_pk_mul_f32 v[138:139], v[140:141], v[178:179]
	v_cvt_pk_bf16_f32 v131, v170, v171
	v_pk_fma_f32 v[138:139], v[132:133], v[180:181], v[138:139] neg_lo:[0,0,1] neg_hi:[0,0,1]
	v_pk_mul_f32 v[132:133], v[132:133], v[178:179]
	v_pk_mul_f32 v[138:139], v[146:147], v[138:139]
	v_pk_fma_f32 v[132:133], v[140:141], v[180:181], v[132:133]
	v_mov_b32_e32 v174, v58
	v_pk_mul_f32 v[140:141], v[146:147], v[132:133]
	v_cvt_pk_bf16_f32 v132, v136, v137
	v_cvt_pk_bf16_f32 v133, v138, v139
	v_cvt_pk_bf16_f32 v136, v142, v143
	v_cvt_pk_bf16_f32 v137, v140, v141
	v_permlane32_swap_b32_e32 v130, v132
	v_permlane32_swap_b32_e32 v131, v133
	v_permlane32_swap_b32_e32 v134, v136
	v_permlane32_swap_b32_e32 v135, v137
	global_store_dwordx4 v[168:169], v[130:133], off
	global_store_dwordx4 v[168:169], v[134:137], off offset:64
	v_mov_b32_e32 v175, v59
	v_mov_b32_e32 v170, v60
	v_mov_b32_e32 v171, v61
	v_mov_b32_e32 v176, v106
	v_mov_b32_e32 v177, v107
	v_mov_b32_e32 v172, v108
	v_mov_b32_e32 v173, v109
	s_and_saveexec_b64 s[8:9], vcc
	s_cbranch_execz .LBB0_356
	global_load_dwordx4 v[138:141], v[148:149], off offset:64
	global_load_dwordx4 v[142:145], v[148:149], off offset:192
	s_waitcnt vmcnt(1)
	v_pk_mul_f32 v[138:139], v[0:1], v[138:139] op_sel_hi:[0,1]
	v_pk_mul_f32 v[140:141], v[0:1], v[140:141] op_sel_hi:[0,1]
	s_waitcnt vmcnt(0)
	v_pk_mul_f32 v[142:143], v[0:1], v[142:143] op_sel_hi:[0,1]
	v_pk_mul_f32 v[144:145], v[0:1], v[144:145] op_sel_hi:[0,1]
	v_pk_mul_f32 v[176:177], v[106:107], v[138:139]
	v_pk_mul_f32 v[172:173], v[108:109], v[140:141]
	v_pk_mul_f32 v[174:175], v[58:59], v[142:143]
	v_pk_mul_f32 v[170:171], v[60:61], v[144:145]
.LBB0_356:
	s_or_b64 exec, exec, s[8:9]
	v_mov_b32_e32 v180, v62
	v_mov_b32_e32 v181, v63
	v_mov_b32_e32 v166, v64
	v_mov_b32_e32 v167, v65
	v_mov_b32_e32 v182, v110
	v_mov_b32_e32 v183, v111
	v_mov_b32_e32 v178, v112
	v_mov_b32_e32 v179, v113
	s_and_saveexec_b64 s[8:9], vcc
	s_cbranch_execz .LBB0_358
	global_load_dwordx4 v[178:181], v[148:149], off offset:96
	global_load_dwordx4 v[194:197], v[148:149], off offset:224
	s_waitcnt vmcnt(1)
	v_pk_mul_f32 v[166:167], v[0:1], v[178:179] op_sel_hi:[0,1]
	v_pk_mul_f32 v[178:179], v[0:1], v[180:181] op_sel_hi:[0,1]
	s_waitcnt vmcnt(0)
	v_pk_mul_f32 v[180:181], v[0:1], v[194:195] op_sel_hi:[0,1]
	v_pk_mul_f32 v[186:187], v[0:1], v[196:197] op_sel_hi:[0,1]
	v_pk_mul_f32 v[182:183], v[110:111], v[166:167]
	v_pk_mul_f32 v[178:179], v[112:113], v[178:179]
	v_pk_mul_f32 v[180:181], v[62:63], v[180:181]
	v_pk_mul_f32 v[166:167], v[64:65], v[186:187]
; template <int EPI>
; DI void phase_gemm(const Params& p, const GemmArgs& ga, char* lds) {
;     ...
;         for (int mi = 0; mi < 4; ++mi) {
;           const int pos = pos0 + wm * 128 + mi * 32 + r;
;           float rs = 1.f;
;           if (nrm) {
;             float ss = 0.f;
; #pragma unroll
;             for (int i = 0; i < 16; ++i) ss += acc[mi][0][i] * acc[mi][0][i] + acc[mi][1][i] * acc[mi][1][i];
;             ss += __shfl_xor(ss, 32);
;             rs = rsqrtf(ss * (1.f / 64.f) + 1e-6f);
;           }
;           u16* q = QK + (size_t)(tokbase + pos) * QK0_LD + dcol + 8 * h;
;           const float* csr = cs + (size_t)pos * 64 + 8 * h;
; #pragma unroll
;           for (int jp = 0; jp < 2; ++jp) {
;             u32x2 v1[2], v2[2];
; #pragma unroll
;             for (int jj = 0; jj < 2; ++jj) {
;               const int j = 2 * jp + jj;
;               const float4 ca = *(const float4*)(csr + 16 * j);
;               const float4 cb = *(const float4*)(csr + 16 * j + 4);
;               float x1[4], x2[4];
; #pragma unroll
;               for (int e = 0; e < 4; ++e) { x1[e] = acc[mi][0][4 * j + e]; x2[e] = acc[mi][1][4 * j + e]; }
;               if (nrm) {
;                 const float4 ga_ = *(const float4*)(gq + 8 * j + 4 * h);
;                 const float4 gb_ = *(const float4*)(gq + 32 + 8 * j + 4 * h);
;                 x1[0] *= rs * ga_.x; x1[1] *= rs * ga_.y; x1[2] *= rs * ga_.z; x1[3] *= rs * ga_.w;
;                 x2[0] *= rs * gb_.x; x2[1] *= rs * gb_.y; x2[2] *= rs * gb_.z; x2[3] *= rs * gb_.w;
;               }
;               const float cc[4] = {ca.x, ca.z, cb.x, cb.z};
;               const float sn[4] = {ca.y, ca.w, cb.y, cb.w};
;               float y1[4], y2[4];
; #pragma unroll
;               for (int e = 0; e < 4; ++e) {
;                 y1[e] = (x1[e] * cc[e] - x2[e] * sn[e]) * osc;
;                 y2[e] = (x2[e] * cc[e] + x1[e] * sn[e]) * osc;
;               }
;               v1[jj] = (u32x2){pk_bf16(y1[0], y1[1]), pk_bf16(y1[2], y1[3])};
;               v2[jj] = (u32x2){pk_bf16(y2[0], y2[1]), pk_bf16(y2[2], y2[3])};
;             }
;             half_swap(v1[0], v1[1]);
;             half_swap(v2[0], v2[1]);
;             u32x4 w1 = {v1[0].x, v1[0].y, v1[1].x, v1[1].y};
;             u32x4 w2 = {v2[0].x, v2[0].y, v2[1].x, v2[1].y};
;             *(u32x4*)(q + 16 * jp) = w1;
;             *(u32x4*)(q + 32 + 16 * jp) = w2;
.LBB0_358:
	s_or_b64 exec, exec, s[8:9]
	s_waitcnt vmcnt(2)
	v_mov_b32_e32 v186, v230
	v_mov_b32_e32 v187, v232
	v_mov_b32_e32 v232, v231
	v_pk_mul_f32 v[230:231], v[232:233], v[174:175]
	v_pk_mul_f32 v[174:175], v[186:187], v[174:175]
	v_pk_fma_f32 v[230:231], v[186:187], v[176:177], v[230:231] neg_lo:[0,0,1] neg_hi:[0,0,1]
	v_pk_fma_f32 v[232:233], v[232:233], v[176:177], v[174:175]
	v_mov_b32_e32 v175, v228
	v_mov_b32_e32 v228, v227
	v_mov_b32_e32 v174, v226
	v_pk_mul_f32 v[226:227], v[228:229], v[170:171]
	v_pk_mul_f32 v[230:231], v[146:147], v[230:231]
	v_pk_fma_f32 v[226:227], v[174:175], v[172:173], v[226:227] neg_lo:[0,0,1] neg_hi:[0,0,1]
	v_pk_mul_f32 v[232:233], v[146:147], v[232:233]
	v_pk_mul_f32 v[176:177], v[146:147], v[226:227]
	v_pk_mul_f32 v[226:227], v[174:175], v[170:171]
	v_mov_b32_e32 v170, v67
	v_pk_fma_f32 v[226:227], v[228:229], v[172:173], v[226:227]
	v_mov_b32_e32 v171, v68
	v_pk_mul_f32 v[228:229], v[146:147], v[226:227]
	v_cvt_pk_bf16_f32 v226, v230, v231
	v_cvt_pk_bf16_f32 v231, v228, v229
	s_waitcnt vmcnt(0)
	v_mov_b32_e32 v229, v240
	v_mov_b32_e32 v240, v239
	v_cvt_pk_bf16_f32 v230, v232, v233
	v_mov_b32_e32 v228, v238
	v_pk_mul_f32 v[232:233], v[240:241], v[180:181]
	v_cvt_pk_bf16_f32 v227, v176, v177
	v_pk_fma_f32 v[232:233], v[228:229], v[182:183], v[232:233] neg_lo:[0,0,1] neg_hi:[0,0,1]
	v_pk_mul_f32 v[228:229], v[228:229], v[180:181]
	v_pk_mul_f32 v[232:233], v[146:147], v[232:233]
	v_pk_fma_f32 v[228:229], v[240:241], v[182:183], v[228:229]
	v_mov_b64_e32 v[172:173], v[18:19]
	v_pk_mul_f32 v[238:239], v[146:147], v[228:229]
	v_mov_b32_e32 v229, v236
	v_mov_b32_e32 v236, v235
	v_mov_b32_e32 v228, v234
	v_pk_mul_f32 v[234:235], v[236:237], v[166:167]
	v_mov_b32_e32 v153, v69
	v_pk_fma_f32 v[234:235], v[228:229], v[178:179], v[234:235] neg_lo:[0,0,1] neg_hi:[0,0,1]
	v_pk_mul_f32 v[228:229], v[228:229], v[166:167]
	v_pk_mul_f32 v[234:235], v[146:147], v[234:235]
	v_pk_fma_f32 v[228:229], v[236:237], v[178:179], v[228:229]
	s_nop 0
	v_pk_mul_f32 v[236:237], v[146:147], v[228:229]
	v_cvt_pk_bf16_f32 v228, v232, v233
	v_cvt_pk_bf16_f32 v229, v234, v235
	v_cvt_pk_bf16_f32 v232, v238, v239
	v_cvt_pk_bf16_f32 v233, v236, v237
	v_permlane32_swap_b32_e32 v226, v228
	v_permlane32_swap_b32_e32 v227, v229
	v_permlane32_swap_b32_e32 v230, v232
	v_permlane32_swap_b32_e32 v231, v233
	global_store_dwordx4 v[168:169], v[226:229], off offset:32
	global_store_dwordx4 v[168:169], v[230:233], off offset:96
	v_mov_b64_e32 v[168:169], v[20:21]
	s_and_saveexec_b64 s[8:9], s[6:7]
	s_xor_b64 s[8:9], exec, s[8:9]
	v_mov_b32_e32 v170, v67
	v_mov_b32_e32 v171, v68
	v_mov_b64_e32 v[168:169], v[20:21]
	v_mov_b64_e32 v[172:173], v[18:19]
	v_mov_b32_e32 v153, v69
	s_or_saveexec_b64 s[12:13], s[8:9]
	v_mov_b32_e32 v0, 1.0
	s_xor_b64 exec, exec, s[12:13]
	s_cbranch_execz .LBB0_362
	v_mul_f32_e32 v0, v66, v66
	v_mul_f32_e32 v130, v67, v67
	v_fmac_f32_e32 v0, v18, v18
	v_fmac_f32_e32 v130, v19, v19
	v_add_f32_e32 v0, v0, v130
	v_mul_f32_e32 v130, v68, v68
	v_fmac_f32_e32 v130, v20, v20
	v_add_f32_e32 v0, v130, v0
	v_mul_f32_e32 v130, v69, v69
	v_fmac_f32_e32 v130, v21, v21
	v_add_f32_e32 v0, v130, v0
	v_mul_f32_e32 v130, v70, v70
	v_fmac_f32_e32 v130, v22, v22
	v_add_f32_e32 v0, v130, v0
	v_mul_f32_e32 v130, v71, v71
	v_fmac_f32_e32 v130, v23, v23
	v_add_f32_e32 v0, v130, v0
	v_pk_mul_f32 v[130:131], v[72:73], v[72:73]
	v_pk_mul_f32 v[132:133], v[74:75], v[74:75]
	v_pk_fma_f32 v[130:131], v[24:25], v[24:25], v[130:131]
	v_pk_fma_f32 v[132:133], v[26:27], v[26:27], v[132:133]
	v_add_f32_e32 v0, v130, v0
	v_add_f32_e32 v0, v131, v0
	v_pk_mul_f32 v[134:135], v[76:77], v[76:77]
	v_add_f32_e32 v0, v132, v0
	v_pk_fma_f32 v[134:135], v[28:29], v[28:29], v[134:135]
	v_add_f32_e32 v0, v133, v0
	v_pk_mul_f32 v[136:137], v[78:79], v[78:79]
	v_add_f32_e32 v0, v134, v0
	v_pk_fma_f32 v[136:137], v[30:31], v[30:31], v[136:137]
	v_add_f32_e32 v0, v135, v0
	v_pk_mul_f32 v[138:139], v[80:81], v[80:81]
	v_add_f32_e32 v0, v136, v0
	v_pk_fma_f32 v[138:139], v[32:33], v[32:33], v[138:139]
	v_add_f32_e32 v0, v137, v0
	v_cmp_lt_i32_e64 s[8:9], v214, v208
	v_add_f32_e32 v0, v138, v0
	v_add_f32_e32 v0, v139, v0
	v_cndmask_b32_e64 v130, v207, v214, s[8:9]
	v_lshlrev_b32_e32 v130, 2, v130
	ds_bpermute_b32 v130, v130, v0
	s_waitcnt lgkmcnt(0)
	v_add_f32_e32 v0, v0, v130
	v_fmamk_f32 v0, v0, 0x3c800000, v205
	v_mul_f32_e32 v130, 0x4b800000, v0
	v_cmp_gt_f32_e64 s[8:9], s49, v0
	s_nop 1
	v_cndmask_b32_e64 v0, v0, v130, s[8:9]
	v_rsq_f32_e32 v0, v0
	s_nop 0
	v_mul_f32_e32 v130, 0x45800000, v0
	v_cndmask_b32_e64 v0, v0, v130, s[8:9]
.LBB0_362:
	s_or_b64 exec, exec, s[12:13]
	v_or_b32_e32 v174, 64, v152
	v_ashrrev_i32_e32 v175, 31, v174
	v_lshlrev_b64 v[130:131], 8, v[174:175]
	v_lshl_add_u64 v[166:167], v[150:151], 0, v[130:131]
	global_load_dwordx4 v[130:133], v[166:167], off offset:16
	global_load_dwordx4 v[134:137], v[166:167], off
	global_load_dwordx4 v[226:229], v[166:167], off offset:144
	global_load_dwordx4 v[230:233], v[166:167], off offset:128
	global_load_dwordx4 v[234:237], v[166:167], off offset:208
	global_load_dwordx4 v[238:241], v[166:167], off offset:192
	global_load_dword v246, v[166:167], off offset:128
	s_movk_i32 s100, 0x2000
	v_add_co_u32_e64 v244, s[8:9], s100, v166
	v_addc_co_u32_e64 v245, s[8:9], 0, v167, s[8:9]
	global_load_dword v247, v[244:245], off
	global_load_dword v248, v[244:245], off offset:128
	v_mov_b32_e32 v176, v66
	s_and_saveexec_b64 s[8:9], vcc
	s_cbranch_execz .LBB0_364
	global_load_dwordx4 v[138:141], v[148:149], off
	s_waitcnt vmcnt(0)
	v_mov_b32_e32 v142, v139
	v_mov_b32_e32 v143, v140
	v_mul_f32_e32 v138, v0, v138
	v_mul_f32_e32 v176, v66, v138
	v_pk_mul_f32 v[138:139], v[0:1], v[142:143] op_sel_hi:[0,1]
	v_pk_mul_f32 v[170:171], v[170:171], v[138:139]
	v_mul_f32_e32 v138, v0, v141
	v_mul_f32_e32 v153, v153, v138
	global_load_dwordx4 v[138:141], v[148:149], off offset:128
	s_waitcnt vmcnt(0)
	v_pk_mul_f32 v[138:139], v[0:1], v[138:139] op_sel_hi:[0,1]
	v_pk_mul_f32 v[172:173], v[172:173], v[138:139]
	v_pk_mul_f32 v[138:139], v[0:1], v[140:141] op_sel_hi:[0,1]
	v_pk_mul_f32 v[168:169], v[168:169], v[138:139]

; template <int EPI>
; DI void phase_gemm(const Params& p, const GemmArgs& ga, char* lds) {
;     ...
;           for (int jp = 0; jp < 2; ++jp) {
;             u32x2 v1[2], v2[2];
; #pragma unroll
;             for (int jj = 0; jj < 2; ++jj) {
;               const int j = 2 * jp + jj;
;               const float4 ca = *(const float4*)(csr + 16 * j);
;               const float4 cb = *(const float4*)(csr + 16 * j + 4);
;               float x1[4], x2[4];
; #pragma unroll
;               for (int e = 0; e < 4; ++e) { x1[e] = acc[mi][0][4 * j + e]; x2[e] = acc[mi][1][4 * j + e]; }
;               if (nrm) {
;                 const float4 ga_ = *(const float4*)(gq + 8 * j + 4 * h);
;                 const float4 gb_ = *(const float4*)(gq + 32 + 8 * j + 4 * h);
;                 x1[0] *= rs * ga_.x; x1[1] *= rs * ga_.y; x1[2] *= rs * ga_.z; x1[3] *= rs * ga_.w;
;                 x2[0] *= rs * gb_.x; x2[1] *= rs * gb_.y; x2[2] *= rs * gb_.z; x2[3] *= rs * gb_.w;
;               }
;               const float cc[4] = {ca.x, ca.z, cb.x, cb.z};
;               const float sn[4] = {ca.y, ca.w, cb.y, cb.w};
;               float y1[4], y2[4];
; #pragma unroll
;               for (int e = 0; e < 4; ++e) {
;                 y1[e] = (x1[e] * cc[e] - x2[e] * sn[e]) * osc;
;                 y2[e] = (x2[e] * cc[e] + x1[e] * sn[e]) * osc;
;               }
;               v1[jj] = (u32x2){pk_bf16(y1[0], y1[1]), pk_bf16(y1[2], y1[3])};
;               v2[jj] = (u32x2){pk_bf16(y2[0], y2[1]), pk_bf16(y2[2], y2[3])};
;             }
;             half_swap(v1[0], v1[1]);
;             half_swap(v2[0], v2[1]);
;             u32x4 w1 = {v1[0].x, v1[0].y, v1[1].x, v1[1].y};
;             u32x4 w2 = {v2[0].x, v2[0].y, v2[1].x, v2[1].y};
;             *(u32x4*)(q + 16 * jp) = w1;
;             *(u32x4*)(q + 32 + 16 * jp) = w2;
.LBB0_366:
	s_or_b64 exec, exec, s[8:9]
	s_waitcnt vmcnt(2)
	v_mov_b32_e32 v195, v136
	v_mov_b32_e32 v197, v136
	v_mov_b32_e32 v136, v135
	v_mov_b32_e32 v194, v135
	v_pk_mov_b32 v[198:199], v[170:171], v[170:171] op_sel:[1,0]
	v_pk_mul_f32 v[200:201], v[136:137], v[172:173]
	v_mov_b32_e32 v135, v137
	v_mov_b32_e32 v137, v132
	v_mov_b32_e32 v132, v131
	v_mov_b32_e32 v196, v134
	v_mov_b32_e32 v177, v199
	v_mov_b32_e32 v136, v130
	v_mov_b32_e32 v199, v153
	v_pk_mul_f32 v[130:131], v[132:133], v[168:169]
	v_pk_fma_f32 v[196:197], v[196:197], v[176:177], v[200:201] neg_lo:[0,0,1] neg_hi:[0,0,1]
	v_mov_b32_e32 v177, v173
	v_pk_fma_f32 v[130:131], v[136:137], v[198:199], v[130:131] neg_lo:[0,0,1] neg_hi:[0,0,1]
	v_pk_mul_f32 v[176:177], v[194:195], v[176:177]
	v_mov_b32_e32 v173, v170
	v_pk_mul_f32 v[170:171], v[146:147], v[130:131]
	v_pk_mul_f32 v[130:131], v[136:137], v[168:169]
	v_pk_fma_f32 v[134:135], v[134:135], v[172:173], v[176:177]
	v_pk_fma_f32 v[130:131], v[132:133], v[198:199], v[130:131]
	v_pk_mul_f32 v[134:135], v[146:147], v[134:135]
	v_pk_mul_f32 v[132:133], v[146:147], v[130:131]
	v_cvt_pk_bf16_f32 v134, v134, v135
	v_cvt_pk_bf16_f32 v135, v132, v133
	v_add_u32_e32 v132, s20, v174
	s_waitcnt vmcnt(0)
	v_mov_b32_e32 v133, v144
	v_mov_b32_e32 v144, v143
	v_mad_i64_i32 v[168:169], s[8:9], v132, s96, v[164:165]
	v_mov_b32_e32 v132, v142
	v_pk_mul_f32 v[136:137], v[144:145], v[182:183]
	v_pk_mul_f32 v[196:197], v[146:147], v[196:197]
	v_pk_fma_f32 v[136:137], v[132:133], v[186:187], v[136:137] neg_lo:[0,0,1] neg_hi:[0,0,1]
	v_pk_mul_f32 v[132:133], v[132:133], v[182:183]
	v_pk_mul_f32 v[136:137], v[146:147], v[136:137]
	v_pk_fma_f32 v[132:133], v[144:145], v[186:187], v[132:133]
	v_cvt_pk_bf16_f32 v130, v196, v197
	v_pk_mul_f32 v[142:143], v[146:147], v[132:133]
	v_mov_b32_e32 v133, v140
	v_mov_b32_e32 v140, v139
	v_mov_b32_e32 v132, v138
	v_pk_mul_f32 v[138:139], v[140:141], v[178:179]
	v_cvt_pk_bf16_f32 v131, v170, v171
	v_pk_fma_f32 v[138:139], v[132:133], v[180:181], v[138:139] neg_lo:[0,0,1] neg_hi:[0,0,1]
	v_pk_mul_f32 v[132:133], v[132:133], v[178:179]
	v_pk_mul_f32 v[138:139], v[146:147], v[138:139]
	v_pk_fma_f32 v[132:133], v[140:141], v[180:181], v[132:133]
	v_mov_b32_e32 v174, v26
	v_pk_mul_f32 v[140:141], v[146:147], v[132:133]
	v_cvt_pk_bf16_f32 v132, v136, v137
	v_cvt_pk_bf16_f32 v133, v138, v139
	v_cvt_pk_bf16_f32 v136, v142, v143
	v_cvt_pk_bf16_f32 v137, v140, v141
	v_permlane32_swap_b32_e32 v130, v132
	v_permlane32_swap_b32_e32 v131, v133
	v_permlane32_swap_b32_e32 v134, v136
	v_permlane32_swap_b32_e32 v135, v137
	global_store_dwordx4 v[168:169], v[130:133], off
	global_store_dwordx4 v[168:169], v[134:137], off offset:64
	v_mov_b32_e32 v175, v27
	v_mov_b32_e32 v170, v28
	v_mov_b32_e32 v171, v29
	v_mov_b32_e32 v176, v74
	v_mov_b32_e32 v177, v75
	v_mov_b32_e32 v172, v76
	v_mov_b32_e32 v173, v77
	s_and_saveexec_b64 s[8:9], vcc
	s_cbranch_execz .LBB0_368
	global_load_dwordx4 v[138:141], v[148:149], off offset:64
	global_load_dwordx4 v[142:145], v[148:149], off offset:192
	s_waitcnt vmcnt(1)
	v_pk_mul_f32 v[138:139], v[0:1], v[138:139] op_sel_hi:[0,1]
	v_pk_mul_f32 v[140:141], v[0:1], v[140:141] op_sel_hi:[0,1]
	s_waitcnt vmcnt(0)
	v_pk_mul_f32 v[142:143], v[0:1], v[142:143] op_sel_hi:[0,1]
	v_pk_mul_f32 v[144:145], v[0:1], v[144:145] op_sel_hi:[0,1]
	v_pk_mul_f32 v[176:177], v[74:75], v[138:139]
	v_pk_mul_f32 v[172:173], v[76:77], v[140:141]
	v_pk_mul_f32 v[174:175], v[26:27], v[142:143]
	v_pk_mul_f32 v[170:171], v[28:29], v[144:145]
.LBB0_368:
	s_or_b64 exec, exec, s[8:9]
	v_mov_b32_e32 v180, v30
	v_mov_b32_e32 v181, v31
	v_mov_b32_e32 v166, v32
	v_mov_b32_e32 v167, v33
	v_mov_b32_e32 v182, v78
	v_mov_b32_e32 v183, v79
	v_mov_b32_e32 v178, v80
	v_mov_b32_e32 v179, v81
	s_and_saveexec_b64 s[8:9], vcc
	s_cbranch_execz .LBB0_370
	global_load_dwordx4 v[178:181], v[148:149], off offset:96
	global_load_dwordx4 v[194:197], v[148:149], off offset:224
	s_waitcnt vmcnt(1)
	v_pk_mul_f32 v[166:167], v[0:1], v[178:179] op_sel_hi:[0,1]
	v_pk_mul_f32 v[178:179], v[0:1], v[180:181] op_sel_hi:[0,1]
	s_waitcnt vmcnt(0)
	v_pk_mul_f32 v[180:181], v[0:1], v[194:195] op_sel_hi:[0,1]
	v_pk_mul_f32 v[186:187], v[0:1], v[196:197] op_sel_hi:[0,1]
	v_pk_mul_f32 v[182:183], v[78:79], v[166:167]
	v_pk_mul_f32 v[178:179], v[80:81], v[178:179]
	v_pk_mul_f32 v[180:181], v[30:31], v[180:181]
	v_pk_mul_f32 v[166:167], v[32:33], v[186:187]
; template <int EPI>
; DI void phase_gemm(const Params& p, const GemmArgs& ga, char* lds) {
;     ...
;         for (int mi = 0; mi < 4; ++mi) {
;           const int pos = pos0 + wm * 128 + mi * 32 + r;
;           float rs = 1.f;
;           if (nrm) {
;             float ss = 0.f;
; #pragma unroll
;             for (int i = 0; i < 16; ++i) ss += acc[mi][0][i] * acc[mi][0][i] + acc[mi][1][i] * acc[mi][1][i];
;             ss += __shfl_xor(ss, 32);
;             rs = rsqrtf(ss * (1.f / 64.f) + 1e-6f);
;           }
;           u16* q = QK + (size_t)(tokbase + pos) * QK0_LD + dcol + 8 * h;
;           const float* csr = cs + (size_t)pos * 64 + 8 * h;
; #pragma unroll
;           for (int jp = 0; jp < 2; ++jp) {
;             u32x2 v1[2], v2[2];
; #pragma unroll
;             for (int jj = 0; jj < 2; ++jj) {
;               const int j = 2 * jp + jj;
;               const float4 ca = *(const float4*)(csr + 16 * j);
;               const float4 cb = *(const float4*)(csr + 16 * j + 4);
;               float x1[4], x2[4];
; #pragma unroll
;               for (int e = 0; e < 4; ++e) { x1[e] = acc[mi][0][4 * j + e]; x2[e] = acc[mi][1][4 * j + e]; }
;               if (nrm) {
;                 const float4 ga_ = *(const float4*)(gq + 8 * j + 4 * h);
;                 const float4 gb_ = *(const float4*)(gq + 32 + 8 * j + 4 * h);
;                 x1[0] *= rs * ga_.x; x1[1] *= rs * ga_.y; x1[2] *= rs * ga_.z; x1[3] *= rs * ga_.w;
;                 x2[0] *= rs * gb_.x; x2[1] *= rs * gb_.y; x2[2] *= rs * gb_.z; x2[3] *= rs * gb_.w;
;               }
;               const float cc[4] = {ca.x, ca.z, cb.x, cb.z};
;               const float sn[4] = {ca.y, ca.w, cb.y, cb.w};
;               float y1[4], y2[4];
; #pragma unroll
;               for (int e = 0; e < 4; ++e) {
;                 y1[e] = (x1[e] * cc[e] - x2[e] * sn[e]) * osc;
;                 y2[e] = (x2[e] * cc[e] + x1[e] * sn[e]) * osc;
;               }
;               v1[jj] = (u32x2){pk_bf16(y1[0], y1[1]), pk_bf16(y1[2], y1[3])};
;               v2[jj] = (u32x2){pk_bf16(y2[0], y2[1]), pk_bf16(y2[2], y2[3])};
;             }
;             half_swap(v1[0], v1[1]);
;             half_swap(v2[0], v2[1]);
;             u32x4 w1 = {v1[0].x, v1[0].y, v1[1].x, v1[1].y};
;             u32x4 w2 = {v2[0].x, v2[0].y, v2[1].x, v2[1].y};
;             *(u32x4*)(q + 16 * jp) = w1;
;             *(u32x4*)(q + 32 + 16 * jp) = w2;
.LBB0_370:
	s_or_b64 exec, exec, s[8:9]
	s_waitcnt vmcnt(2)
	v_mov_b32_e32 v186, v230
	v_mov_b32_e32 v187, v232
	v_mov_b32_e32 v232, v231
	v_pk_mul_f32 v[230:231], v[232:233], v[174:175]
	v_pk_mul_f32 v[174:175], v[186:187], v[174:175]
	v_pk_fma_f32 v[230:231], v[186:187], v[176:177], v[230:231] neg_lo:[0,0,1] neg_hi:[0,0,1]
	v_pk_fma_f32 v[232:233], v[232:233], v[176:177], v[174:175]
	v_mov_b32_e32 v175, v228
	v_mov_b32_e32 v228, v227
	v_mov_b32_e32 v174, v226
	v_pk_mul_f32 v[226:227], v[228:229], v[170:171]
	v_pk_mul_f32 v[230:231], v[146:147], v[230:231]
	v_pk_fma_f32 v[226:227], v[174:175], v[172:173], v[226:227] neg_lo:[0,0,1] neg_hi:[0,0,1]
	v_pk_mul_f32 v[232:233], v[146:147], v[232:233]
	v_pk_mul_f32 v[176:177], v[146:147], v[226:227]
	v_pk_mul_f32 v[226:227], v[174:175], v[170:171]
	v_mov_b64_e32 v[170:171], v[2:3]
	v_pk_fma_f32 v[226:227], v[228:229], v[172:173], v[226:227]
	v_mov_b32_e32 v161, v37
	v_pk_mul_f32 v[228:229], v[146:147], v[226:227]
	v_cvt_pk_bf16_f32 v226, v230, v231
	v_cvt_pk_bf16_f32 v231, v228, v229
	s_waitcnt vmcnt(0)
	v_mov_b32_e32 v229, v240
	v_mov_b32_e32 v240, v239
	v_cvt_pk_bf16_f32 v230, v232, v233
	v_mov_b32_e32 v228, v238
	v_pk_mul_f32 v[232:233], v[240:241], v[180:181]
	v_cvt_pk_bf16_f32 v227, v176, v177
	v_pk_fma_f32 v[232:233], v[228:229], v[182:183], v[232:233] neg_lo:[0,0,1] neg_hi:[0,0,1]
	v_pk_mul_f32 v[228:229], v[228:229], v[180:181]
	v_pk_mul_f32 v[232:233], v[146:147], v[232:233]
	v_pk_fma_f32 v[228:229], v[240:241], v[182:183], v[228:229]
	s_nop 0
	v_pk_mul_f32 v[238:239], v[146:147], v[228:229]
	v_mov_b32_e32 v229, v236
	v_mov_b32_e32 v236, v235
	v_mov_b32_e32 v228, v234
	v_pk_mul_f32 v[234:235], v[236:237], v[166:167]
	s_nop 0
	v_pk_fma_f32 v[234:235], v[228:229], v[178:179], v[234:235] neg_lo:[0,0,1] neg_hi:[0,0,1]
	v_pk_mul_f32 v[228:229], v[228:229], v[166:167]
	v_pk_mul_f32 v[234:235], v[146:147], v[234:235]
	v_pk_fma_f32 v[228:229], v[236:237], v[178:179], v[228:229]
	v_mov_b64_e32 v[166:167], v[4:5]
	v_pk_mul_f32 v[236:237], v[146:147], v[228:229]
	v_cvt_pk_bf16_f32 v228, v232, v233
	v_cvt_pk_bf16_f32 v229, v234, v235
	v_cvt_pk_bf16_f32 v232, v238, v239
	v_cvt_pk_bf16_f32 v233, v236, v237
	v_permlane32_swap_b32_e32 v226, v228
	v_permlane32_swap_b32_e32 v227, v229
	v_permlane32_swap_b32_e32 v230, v232
	v_permlane32_swap_b32_e32 v231, v233
	global_store_dwordx4 v[168:169], v[226:229], off offset:32
	global_store_dwordx4 v[168:169], v[230:233], off offset:96
	v_mov_b32_e32 v168, v35
	v_mov_b32_e32 v169, v36
	s_and_saveexec_b64 s[8:9], s[6:7]
	s_xor_b64 s[6:7], exec, s[8:9]
	v_mov_b32_e32 v168, v35
	v_mov_b32_e32 v169, v36
	v_mov_b64_e32 v[166:167], v[4:5]
	v_mov_b64_e32 v[170:171], v[2:3]
	v_mov_b32_e32 v161, v37
	s_or_saveexec_b64 s[8:9], s[6:7]
	v_mov_b32_e32 v0, 1.0
	s_xor_b64 exec, exec, s[8:9]
	s_cbranch_execz .LBB0_374
	v_mul_f32_e32 v0, v34, v34
	v_mul_f32_e32 v130, v35, v35
	v_fmac_f32_e32 v0, v2, v2
	v_fmac_f32_e32 v130, v3, v3
	v_add_f32_e32 v0, v0, v130
	v_mul_f32_e32 v130, v36, v36
	v_fmac_f32_e32 v130, v4, v4
	v_add_f32_e32 v0, v130, v0
	v_mul_f32_e32 v130, v37, v37
	v_fmac_f32_e32 v130, v5, v5
	v_add_f32_e32 v0, v130, v0
	v_mul_f32_e32 v130, v38, v38
	v_fmac_f32_e32 v130, v6, v6
	v_add_f32_e32 v0, v130, v0
	v_mul_f32_e32 v130, v39, v39
	v_fmac_f32_e32 v130, v7, v7
	v_add_f32_e32 v0, v130, v0
	v_pk_mul_f32 v[130:131], v[40:41], v[40:41]
	v_pk_mul_f32 v[132:133], v[42:43], v[42:43]
	v_pk_fma_f32 v[130:131], v[8:9], v[8:9], v[130:131]
	v_pk_fma_f32 v[132:133], v[10:11], v[10:11], v[132:133]
	v_add_f32_e32 v0, v130, v0
	v_add_f32_e32 v0, v131, v0
	v_pk_mul_f32 v[134:135], v[44:45], v[44:45]
	v_add_f32_e32 v0, v132, v0
	v_pk_fma_f32 v[134:135], v[12:13], v[12:13], v[134:135]
	v_add_f32_e32 v0, v133, v0
	v_pk_mul_f32 v[136:137], v[46:47], v[46:47]
	v_add_f32_e32 v0, v134, v0
	v_pk_fma_f32 v[136:137], v[14:15], v[14:15], v[136:137]
	v_add_f32_e32 v0, v135, v0
	v_pk_mul_f32 v[138:139], v[48:49], v[48:49]
	v_add_f32_e32 v0, v136, v0
	v_pk_fma_f32 v[138:139], v[16:17], v[16:17], v[138:139]
	v_add_f32_e32 v0, v137, v0
	v_cmp_lt_i32_e64 s[6:7], v214, v208
	v_add_f32_e32 v0, v138, v0
	v_add_f32_e32 v0, v139, v0
	v_cndmask_b32_e64 v130, v207, v214, s[6:7]
	v_lshlrev_b32_e32 v130, 2, v130
	ds_bpermute_b32 v130, v130, v0
	s_waitcnt lgkmcnt(0)
	v_add_f32_e32 v0, v0, v130
	v_fmamk_f32 v0, v0, 0x3c800000, v205
	v_mul_f32_e32 v130, 0x4b800000, v0
	v_cmp_gt_f32_e64 s[6:7], s49, v0
	s_nop 1
	v_cndmask_b32_e64 v0, v0, v130, s[6:7]
	v_rsq_f32_e32 v0, v0
	s_nop 0
	v_mul_f32_e32 v130, 0x45800000, v0
	v_cndmask_b32_e64 v0, v0, v130, s[6:7]
.LBB0_374:
	s_or_b64 exec, exec, s[8:9]
	v_or_b32_e32 v152, 0x60, v152
	v_ashrrev_i32_e32 v153, 31, v152
	v_lshlrev_b64 v[130:131], 8, v[152:153]
	v_lshl_add_u64 v[150:151], v[150:151], 0, v[130:131]
	global_load_dwordx4 v[130:133], v[150:151], off offset:16
	global_load_dwordx4 v[134:137], v[150:151], off
	global_load_dwordx4 v[226:229], v[150:151], off offset:144
	global_load_dwordx4 v[230:233], v[150:151], off offset:128
	global_load_dwordx4 v[234:237], v[150:151], off offset:208
	global_load_dwordx4 v[238:241], v[150:151], off offset:192
	global_load_dword v246, v[150:151], off offset:128
	v_mov_b32_e32 v172, v34
	s_and_saveexec_b64 s[6:7], vcc
	s_cbranch_execz .LBB0_376
	global_load_dwordx4 v[138:141], v[148:149], off
	s_waitcnt vmcnt(0)
	v_mov_b32_e32 v142, v139
	v_mov_b32_e32 v143, v140
	v_mul_f32_e32 v138, v0, v138
	v_mul_f32_e32 v172, v34, v138
	v_pk_mul_f32 v[138:139], v[0:1], v[142:143] op_sel_hi:[0,1]
	v_pk_mul_f32 v[168:169], v[168:169], v[138:139]
	v_mul_f32_e32 v138, v0, v141
	v_mul_f32_e32 v161, v161, v138
	global_load_dwordx4 v[138:141], v[148:149], off offset:128
	s_waitcnt vmcnt(0)
	v_pk_mul_f32 v[138:139], v[0:1], v[138:139] op_sel_hi:[0,1]
	v_pk_mul_f32 v[170:171], v[170:171], v[138:139]
	v_pk_mul_f32 v[138:139], v[0:1], v[140:141] op_sel_hi:[0,1]
	v_pk_mul_f32 v[166:167], v[166:167], v[138:139]

; template <int EPI>
; DI void phase_gemm(const Params& p, const GemmArgs& ga, char* lds) {
;     ...
;           for (int jp = 0; jp < 2; ++jp) {
;             u32x2 v1[2], v2[2];
; #pragma unroll
;             for (int jj = 0; jj < 2; ++jj) {
;               const int j = 2 * jp + jj;
;               const float4 ca = *(const float4*)(csr + 16 * j);
;               const float4 cb = *(const float4*)(csr + 16 * j + 4);
;               float x1[4], x2[4];
; #pragma unroll
;               for (int e = 0; e < 4; ++e) { x1[e] = acc[mi][0][4 * j + e]; x2[e] = acc[mi][1][4 * j + e]; }
;               if (nrm) {
;                 const float4 ga_ = *(const float4*)(gq + 8 * j + 4 * h);
;                 const float4 gb_ = *(const float4*)(gq + 32 + 8 * j + 4 * h);
;                 x1[0] *= rs * ga_.x; x1[1] *= rs * ga_.y; x1[2] *= rs * ga_.z; x1[3] *= rs * ga_.w;
;                 x2[0] *= rs * gb_.x; x2[1] *= rs * gb_.y; x2[2] *= rs * gb_.z; x2[3] *= rs * gb_.w;
;               }
;               const float cc[4] = {ca.x, ca.z, cb.x, cb.z};
;               const float sn[4] = {ca.y, ca.w, cb.y, cb.w};
;               float y1[4], y2[4];
; #pragma unroll
;               for (int e = 0; e < 4; ++e) {
;                 y1[e] = (x1[e] * cc[e] - x2[e] * sn[e]) * osc;
;                 y2[e] = (x2[e] * cc[e] + x1[e] * sn[e]) * osc;
;               }
;               v1[jj] = (u32x2){pk_bf16(y1[0], y1[1]), pk_bf16(y1[2], y1[3])};
;               v2[jj] = (u32x2){pk_bf16(y2[0], y2[1]), pk_bf16(y2[2], y2[3])};
;             }
;             half_swap(v1[0], v1[1]);
;             half_swap(v2[0], v2[1]);
;             u32x4 w1 = {v1[0].x, v1[0].y, v1[1].x, v1[1].y};
;             u32x4 w2 = {v2[0].x, v2[0].y, v2[1].x, v2[1].y};
;             *(u32x4*)(q + 16 * jp) = w1;
;             *(u32x4*)(q + 32 + 16 * jp) = w2;
.LBB0_378:
	s_or_b64 exec, exec, s[6:7]
	s_waitcnt vmcnt(2)
	v_mov_b32_e32 v183, v136
	v_mov_b32_e32 v187, v136
	v_mov_b32_e32 v136, v135
	v_mov_b32_e32 v182, v135
	v_pk_mov_b32 v[194:195], v[168:169], v[168:169] op_sel:[1,0]
	v_pk_mul_f32 v[196:197], v[136:137], v[170:171]
	v_mov_b32_e32 v135, v137
	v_mov_b32_e32 v137, v132
	v_mov_b32_e32 v132, v131
	v_mov_b32_e32 v186, v134
	v_mov_b32_e32 v173, v195
	v_mov_b32_e32 v136, v130
	v_mov_b32_e32 v195, v161
	v_pk_mul_f32 v[130:131], v[132:133], v[166:167]
	v_pk_fma_f32 v[186:187], v[186:187], v[172:173], v[196:197] neg_lo:[0,0,1] neg_hi:[0,0,1]
	v_mov_b32_e32 v173, v171
	v_pk_fma_f32 v[130:131], v[136:137], v[194:195], v[130:131] neg_lo:[0,0,1] neg_hi:[0,0,1]
	v_pk_mul_f32 v[172:173], v[182:183], v[172:173]
	v_mov_b32_e32 v171, v168
	v_pk_mul_f32 v[168:169], v[146:147], v[130:131]
	v_pk_mul_f32 v[130:131], v[136:137], v[166:167]
	v_pk_fma_f32 v[134:135], v[134:135], v[170:171], v[172:173]
	v_pk_fma_f32 v[130:131], v[132:133], v[194:195], v[130:131]
	v_pk_mul_f32 v[134:135], v[146:147], v[134:135]
	v_pk_mul_f32 v[132:133], v[146:147], v[130:131]
	v_cvt_pk_bf16_f32 v134, v134, v135
	v_cvt_pk_bf16_f32 v135, v132, v133
	v_add_u32_e32 v132, s20, v152
	s_waitcnt vmcnt(0)
	v_mov_b32_e32 v133, v144
	v_mov_b32_e32 v144, v143
	v_mad_i64_i32 v[152:153], s[6:7], v132, s96, v[164:165]
	v_mov_b32_e32 v132, v142
	v_pk_mul_f32 v[136:137], v[144:145], v[178:179]
	v_pk_mul_f32 v[186:187], v[146:147], v[186:187]
	v_pk_fma_f32 v[136:137], v[132:133], v[180:181], v[136:137] neg_lo:[0,0,1] neg_hi:[0,0,1]
	v_pk_mul_f32 v[132:133], v[132:133], v[178:179]
	v_pk_mul_f32 v[136:137], v[146:147], v[136:137]
	v_pk_fma_f32 v[132:133], v[144:145], v[180:181], v[132:133]
	v_cvt_pk_bf16_f32 v130, v186, v187
	v_pk_mul_f32 v[142:143], v[146:147], v[132:133]
	v_mov_b32_e32 v133, v140
	v_mov_b32_e32 v140, v139
	v_mov_b32_e32 v132, v138
	v_pk_mul_f32 v[138:139], v[140:141], v[174:175]
	v_cvt_pk_bf16_f32 v131, v168, v169
	v_pk_fma_f32 v[138:139], v[132:133], v[176:177], v[138:139] neg_lo:[0,0,1] neg_hi:[0,0,1]
	v_pk_mul_f32 v[132:133], v[132:133], v[174:175]
	v_pk_mul_f32 v[138:139], v[146:147], v[138:139]
	v_pk_fma_f32 v[132:133], v[140:141], v[176:177], v[132:133]
	v_mov_b32_e32 v168, v10
	v_pk_mul_f32 v[140:141], v[146:147], v[132:133]
	v_cvt_pk_bf16_f32 v132, v136, v137
	v_cvt_pk_bf16_f32 v133, v138, v139
	v_cvt_pk_bf16_f32 v136, v142, v143
	v_cvt_pk_bf16_f32 v137, v140, v141
	v_permlane32_swap_b32_e32 v130, v132
	v_permlane32_swap_b32_e32 v131, v133
	v_permlane32_swap_b32_e32 v134, v136
	v_permlane32_swap_b32_e32 v135, v137
	global_store_dwordx4 v[152:153], v[130:133], off
	global_store_dwordx4 v[152:153], v[134:137], off offset:64
	v_mov_b32_e32 v169, v11
	v_mov_b32_e32 v164, v12
	v_mov_b32_e32 v165, v13
	v_mov_b32_e32 v170, v42
	v_mov_b32_e32 v171, v43
	v_mov_b32_e32 v166, v44
	v_mov_b32_e32 v167, v45
	s_and_saveexec_b64 s[6:7], vcc
	s_cbranch_execz .LBB0_380
	global_load_dwordx4 v[138:141], v[148:149], off offset:64
	global_load_dwordx4 v[142:145], v[148:149], off offset:192
	s_waitcnt vmcnt(1)
	v_pk_mul_f32 v[138:139], v[0:1], v[138:139] op_sel_hi:[0,1]
	v_pk_mul_f32 v[140:141], v[0:1], v[140:141] op_sel_hi:[0,1]
	s_waitcnt vmcnt(0)
	v_pk_mul_f32 v[142:143], v[0:1], v[142:143] op_sel_hi:[0,1]
	v_pk_mul_f32 v[144:145], v[0:1], v[144:145] op_sel_hi:[0,1]
	v_pk_mul_f32 v[170:171], v[42:43], v[138:139]
	v_pk_mul_f32 v[166:167], v[44:45], v[140:141]
	v_pk_mul_f32 v[168:169], v[10:11], v[142:143]
	v_pk_mul_f32 v[164:165], v[12:13], v[144:145]
.LBB0_380:
	s_or_b64 exec, exec, s[6:7]
	v_mov_b32_e32 v174, v14
	v_mov_b32_e32 v175, v15
	v_mov_b32_e32 v150, v16
	v_mov_b32_e32 v151, v17
	v_mov_b32_e32 v176, v46
	v_mov_b32_e32 v177, v47
	v_mov_b32_e32 v172, v48
	v_mov_b32_e32 v173, v49
	s_and_saveexec_b64 s[6:7], vcc
	s_cbranch_execz .LBB0_382
	global_load_dwordx4 v[172:175], v[148:149], off offset:96
	s_nop 0
	global_load_dwordx4 v[148:151], v[148:149], off offset:224
	s_waitcnt vmcnt(1)
	v_pk_mul_f32 v[172:173], v[0:1], v[172:173] op_sel_hi:[0,1]
	v_pk_mul_f32 v[174:175], v[0:1], v[174:175] op_sel_hi:[0,1]
	s_waitcnt vmcnt(0)
	v_pk_mul_f32 v[148:149], v[0:1], v[148:149] op_sel_hi:[0,1]
	v_pk_mul_f32 v[150:151], v[0:1], v[150:151] op_sel_hi:[0,1]
	v_pk_mul_f32 v[176:177], v[46:47], v[172:173]
	v_pk_mul_f32 v[172:173], v[48:49], v[174:175]
	v_pk_mul_f32 v[174:175], v[14:15], v[148:149]
	v_pk_mul_f32 v[150:151], v[16:17], v[150:151]
.LBB0_382:
	s_or_b64 exec, exec, s[6:7]
	s_waitcnt vmcnt(2)
	v_mov_b32_e32 v149, v232
	v_mov_b32_e32 v232, v231
	v_mov_b32_e32 v148, v230
	v_pk_mul_f32 v[230:231], v[232:233], v[168:169]
	s_nop 0
	v_pk_fma_f32 v[230:231], v[148:149], v[170:171], v[230:231] neg_lo:[0,0,1] neg_hi:[0,0,1]
	v_pk_mul_f32 v[148:149], v[148:149], v[168:169]
	v_pk_mul_f32 v[230:231], v[146:147], v[230:231]
	v_pk_fma_f32 v[232:233], v[232:233], v[170:171], v[148:149]
	v_mov_b32_e32 v149, v228
	v_mov_b32_e32 v228, v227
	v_mov_b32_e32 v148, v226
	v_pk_mul_f32 v[226:227], v[228:229], v[164:165]
	v_pk_mul_f32 v[232:233], v[146:147], v[232:233]
	v_pk_fma_f32 v[226:227], v[148:149], v[166:167], v[226:227] neg_lo:[0,0,1] neg_hi:[0,0,1]
	s_nop 0
	v_pk_mul_f32 v[168:169], v[146:147], v[226:227]
	v_pk_mul_f32 v[226:227], v[148:149], v[164:165]
	s_nop 0
	v_pk_fma_f32 v[226:227], v[228:229], v[166:167], v[226:227]
	s_nop 0
	v_pk_mul_f32 v[228:229], v[146:147], v[226:227]
	v_cvt_pk_bf16_f32 v226, v230, v231
	v_cvt_pk_bf16_f32 v231, v228, v229
	s_waitcnt vmcnt(0)
	v_mov_b32_e32 v229, v240
	v_mov_b32_e32 v240, v239
	v_cvt_pk_bf16_f32 v230, v232, v233
	v_mov_b32_e32 v228, v238
	v_pk_mul_f32 v[232:233], v[240:241], v[174:175]
	v_cvt_pk_bf16_f32 v227, v168, v169
	v_pk_fma_f32 v[232:233], v[228:229], v[176:177], v[232:233] neg_lo:[0,0,1] neg_hi:[0,0,1]
	v_pk_mul_f32 v[228:229], v[228:229], v[174:175]
	v_pk_mul_f32 v[232:233], v[146:147], v[232:233]
	v_pk_fma_f32 v[228:229], v[240:241], v[176:177], v[228:229]
	s_nop 0
	v_pk_mul_f32 v[238:239], v[146:147], v[228:229]
	v_mov_b32_e32 v229, v236
	v_mov_b32_e32 v236, v235
	v_mov_b32_e32 v228, v234
	v_pk_mul_f32 v[234:235], v[236:237], v[150:151]
	s_nop 0
	v_pk_fma_f32 v[234:235], v[228:229], v[172:173], v[234:235] neg_lo:[0,0,1] neg_hi:[0,0,1]
	v_pk_mul_f32 v[228:229], v[228:229], v[150:151]
	v_pk_mul_f32 v[234:235], v[146:147], v[234:235]
	v_pk_fma_f32 v[228:229], v[236:237], v[172:173], v[228:229]
	s_nop 0
	v_pk_mul_f32 v[236:237], v[146:147], v[228:229]
	v_cvt_pk_bf16_f32 v228, v232, v233
	v_cvt_pk_bf16_f32 v229, v234, v235
	v_cvt_pk_bf16_f32 v232, v238, v239
	v_cvt_pk_bf16_f32 v233, v236, v237
	v_permlane32_swap_b32_e32 v226, v228
	v_permlane32_swap_b32_e32 v227, v229
	v_permlane32_swap_b32_e32 v230, v232
	v_permlane32_swap_b32_e32 v231, v233
	global_store_dwordx4 v[152:153], v[226:229], off offset:32
	global_store_dwordx4 v[152:153], v[230:233], off offset:96
